# S5 chunk scan rewritten (fused multiply-adds, LDS reads of the next half-block run ahead)
# speedup vs baseline: 1.0996x; 1.0069x over previous
.LBB0_500:
	v_add_u32_e32 v45, 0x10000, v44
	v_add_u32_e32 v50, 0x10000, v39
	ds_read_b32 v46, v45
	ds_read_b32 v47, v45 offset:256
	ds_read_b32 v48, v45 offset:512
	ds_read_b32 v49, v45 offset:768
	ds_read_b32 v51, v45 offset:1024
	ds_read_b32 v52, v45 offset:1280
	ds_read_b32 v53, v45 offset:1536
	ds_read_b32 v54, v45 offset:1792
	s_waitcnt lgkmcnt(0)
.Lscan_loop:
	s_waitcnt lgkmcnt(8)
	ds_read_b32 v55, v45 offset:2048
	ds_read_b32 v56, v45 offset:2304
	ds_read_b32 v57, v45 offset:2560
	ds_read_b32 v58, v45 offset:2816
	ds_read_b32 v59, v45 offset:3072
	ds_read_b32 v60, v45 offset:3328
	ds_read_b32 v61, v45 offset:3584
	ds_read_b32 v62, v45 offset:3840
	v_cvt_pk_bf16_f32 v161, v36, v37
	v_fma_f32 v159, v32, v36, v46
	v_fma_f32 v160, v32, v37, v47
	ds_write_b16 v50, v161
	ds_write_b16_d16_hi v50, v161 offset:128
	v_fma_f32 v157, -v33, v37, v159
	v_fma_f32 v158, v33, v36, v160
	v_cvt_pk_bf16_f32 v161, v157, v158
	v_fma_f32 v159, v32, v157, v48
	v_fma_f32 v160, v32, v158, v49
	ds_write_b16 v50, v161 offset:512
	ds_write_b16_d16_hi v50, v161 offset:640
	v_fma_f32 v36, -v33, v158, v159
	v_fma_f32 v37, v33, v157, v160
	v_cvt_pk_bf16_f32 v161, v36, v37
	v_fma_f32 v159, v32, v36, v51
	v_fma_f32 v160, v32, v37, v52
	ds_write_b16 v50, v161 offset:1024
	ds_write_b16_d16_hi v50, v161 offset:1152
	v_fma_f32 v157, -v33, v37, v159
	v_fma_f32 v158, v33, v36, v160
	v_cvt_pk_bf16_f32 v161, v157, v158
	v_fma_f32 v159, v32, v157, v53
	v_fma_f32 v160, v32, v158, v54
	ds_write_b16 v50, v161 offset:1536
	ds_write_b16_d16_hi v50, v161 offset:1664
	v_fma_f32 v36, -v33, v158, v159
	v_fma_f32 v37, v33, v157, v160
	s_waitcnt lgkmcnt(8)
	ds_read_b32 v46, v45 offset:4096
	ds_read_b32 v47, v45 offset:4352
	ds_read_b32 v48, v45 offset:4608
	ds_read_b32 v49, v45 offset:4864
	ds_read_b32 v51, v45 offset:5120
	ds_read_b32 v52, v45 offset:5376
	ds_read_b32 v53, v45 offset:5632
	ds_read_b32 v54, v45 offset:5888
	v_cvt_pk_bf16_f32 v161, v36, v37
	v_fma_f32 v159, v32, v36, v55
	v_fma_f32 v160, v32, v37, v56
	ds_write_b16 v50, v161 offset:2048
	ds_write_b16_d16_hi v50, v161 offset:2176
	v_fma_f32 v157, -v33, v37, v159
	v_fma_f32 v158, v33, v36, v160
	v_cvt_pk_bf16_f32 v161, v157, v158
	v_fma_f32 v159, v32, v157, v57
	v_fma_f32 v160, v32, v158, v58
	ds_write_b16 v50, v161 offset:2560
	ds_write_b16_d16_hi v50, v161 offset:2688
	v_fma_f32 v36, -v33, v158, v159
	v_fma_f32 v37, v33, v157, v160
	v_cvt_pk_bf16_f32 v161, v36, v37
	v_fma_f32 v159, v32, v36, v59
	v_fma_f32 v160, v32, v37, v60
	ds_write_b16 v50, v161 offset:3072
	ds_write_b16_d16_hi v50, v161 offset:3200
	v_fma_f32 v157, -v33, v37, v159
	v_fma_f32 v158, v33, v36, v160
	v_cvt_pk_bf16_f32 v161, v157, v158
	v_fma_f32 v159, v32, v157, v61
	v_fma_f32 v160, v32, v158, v62
	ds_write_b16 v50, v161 offset:3584
	ds_write_b16_d16_hi v50, v161 offset:3712
	v_fma_f32 v36, -v33, v158, v159
	v_fma_f32 v37, v33, v157, v160
	v_add_u32_e32 v45, 0x1000, v45
	v_add_u32_e32 v50, 0x1000, v50
	s_add_i32 s0, s0, 8
	s_cmpk_lt_u32 s0, 0x78
	s_cbranch_scc1 .Lscan_loop
	s_waitcnt lgkmcnt(0)
